# v14 + P7 epilogue counted vmcnt(16), removed per-unit vmcnt(0) drains in P45/P6/P7/P8 unit headers
# baseline (speedup 1.0000x reference)
.LBB0_819:
	v_mov_b32_e32 v2, v0
	v_mov_b32_e32 v3, v0
	s_add_u32 s58, s30, 0x100
	v_mov_b32_e32 v1, v0
	v_mov_b64_e32 v[6:7], v[2:3]
	v_mov_b64_e32 v[10:11], v[2:3]
	v_mov_b64_e32 v[22:23], v[2:3]
	v_mov_b64_e32 v[26:27], v[2:3]
	v_mov_b64_e32 v[38:39], v[2:3]
	v_mov_b64_e32 v[42:43], v[2:3]
	v_mov_b64_e32 v[54:55], v[2:3]
	v_mov_b64_e32 v[58:59], v[2:3]
	v_mov_b64_e32 v[14:15], v[2:3]
	v_mov_b64_e32 v[18:19], v[2:3]
	v_mov_b64_e32 v[30:31], v[2:3]
	v_mov_b64_e32 v[34:35], v[2:3]
	v_mov_b64_e32 v[46:47], v[2:3]
	v_mov_b64_e32 v[50:51], v[2:3]
	v_mov_b64_e32 v[62:63], v[2:3]
	v_mov_b64_e32 v[66:67], v[2:3]
	v_mov_b64_e32 v[70:71], v[2:3]
	v_mov_b64_e32 v[74:75], v[2:3]
	v_mov_b64_e32 v[86:87], v[2:3]
	v_mov_b64_e32 v[90:91], v[2:3]
	s_nop 0
	v_mov_b64_e32 v[102:103], v[2:3]
	v_mov_b64_e32 v[106:107], v[2:3]
	v_mov_b64_e32 v[114:115], v[2:3]
	v_mov_b64_e32 v[118:119], v[2:3]
	v_mov_b64_e32 v[78:79], v[2:3]
	v_mov_b64_e32 v[82:83], v[2:3]
	v_mov_b64_e32 v[94:95], v[2:3]
	v_mov_b64_e32 v[98:99], v[2:3]
	v_mov_b64_e32 v[110:111], v[2:3]
	v_mov_b64_e32 v[122:123], v[2:3]
	v_mov_b64_e32 v[126:127], v[2:3]
	v_mov_b64_e32 v[130:131], v[2:3]
	v_lshl_add_u32 v184, s34, 8, v195
	v_lshl_or_b32 v186, s35, 8, v197
	v_lshl_add_u64 v[188:189], s[28:29], 0, v[176:177]
	v_lshl_add_u64 v[190:191], s[28:29], 0, v[178:179]
	s_addc_u32 s59, s31, 0
	s_mov_b32 s60, -2
	s_mov_b64 s[30:31], 0
	v_mov_b64_e32 v[4:5], v[0:1]
	v_mov_b64_e32 v[8:9], v[0:1]
	v_mov_b64_e32 v[20:21], v[0:1]
	v_mov_b64_e32 v[24:25], v[0:1]
	v_mov_b64_e32 v[36:37], v[0:1]
	v_mov_b64_e32 v[40:41], v[0:1]
	v_mov_b64_e32 v[52:53], v[0:1]
	v_mov_b64_e32 v[56:57], v[0:1]
	v_mov_b64_e32 v[12:13], v[0:1]
	v_mov_b64_e32 v[16:17], v[0:1]
	v_mov_b64_e32 v[28:29], v[0:1]
	v_mov_b64_e32 v[32:33], v[0:1]
	v_mov_b64_e32 v[44:45], v[0:1]
	v_mov_b64_e32 v[48:49], v[0:1]
	v_mov_b64_e32 v[60:61], v[0:1]
	v_mov_b64_e32 v[64:65], v[0:1]
	v_mov_b64_e32 v[68:69], v[0:1]
	v_mov_b64_e32 v[72:73], v[0:1]
	v_mov_b64_e32 v[84:85], v[0:1]
	v_mov_b64_e32 v[88:89], v[0:1]
	v_mov_b64_e32 v[100:101], v[0:1]
	v_mov_b64_e32 v[104:105], v[0:1]
	v_mov_b64_e32 v[112:113], v[0:1]
	v_mov_b64_e32 v[116:117], v[0:1]
	v_mov_b64_e32 v[76:77], v[0:1]
	v_mov_b64_e32 v[80:81], v[0:1]
	v_mov_b64_e32 v[92:93], v[0:1]
	v_mov_b64_e32 v[96:97], v[0:1]
	v_mov_b64_e32 v[108:109], v[0:1]
	v_mov_b64_e32 v[120:121], v[0:1]
	v_mov_b64_e32 v[124:125], v[0:1]
	v_mov_b64_e32 v[128:129], v[0:1]
	s_branch .LBB0_821

.LBB0_899:
	s_ashr_i32 s15, s14, 31
	s_lshl_b64 s[16:17], s[14:15], 19
	s_add_u32 s16, s86, s16
	s_addc_u32 s17, s87, s17
	s_and_b64 s[18:19], s[6:7], exec
	s_cselect_b32 s15, s17, s25
	s_cselect_b32 s21, s16, s24
	s_ashr_i32 s13, s12, 31
	s_lshl_b64 s[18:19], s[12:13], 19
	s_add_u32 s18, s80, s18
	s_addc_u32 s19, s81, s19
	s_and_b64 s[28:29], s[6:7], exec
	s_cselect_b32 s13, s19, s27
	s_cselect_b32 s43, s18, s26
	s_add_u32 s24, s24, 0x40080
	s_addc_u32 s25, s25, 0
	s_add_u32 s44, s26, 0x100
	v_mov_b32_e32 v0, 0
	s_addc_u32 s45, s27, 0
	s_mov_b32 s46, -2
	s_waitcnt lgkmcnt(0)
	v_mov_b32_e32 v1, v0
	v_mov_b32_e32 v2, v0
	v_mov_b32_e32 v3, v0
	v_mov_b32_e32 v4, v0
	v_mov_b32_e32 v5, v0
	v_mov_b32_e32 v6, v0
	v_mov_b32_e32 v7, v0
	v_mov_b32_e32 v16, v0
	v_mov_b32_e32 v17, v0
	v_mov_b32_e32 v18, v0
	v_mov_b32_e32 v19, v0
	v_mov_b32_e32 v20, v0
	v_mov_b32_e32 v21, v0
	v_mov_b32_e32 v22, v0
	v_mov_b32_e32 v23, v0
	v_mov_b32_e32 v32, v0
	v_mov_b32_e32 v33, v0
	v_mov_b32_e32 v34, v0
	v_mov_b32_e32 v35, v0
	v_mov_b32_e32 v36, v0
	v_mov_b32_e32 v37, v0
	v_mov_b32_e32 v38, v0
	v_mov_b32_e32 v39, v0
	v_mov_b32_e32 v48, v0
	v_mov_b32_e32 v49, v0
	v_mov_b32_e32 v50, v0
	v_mov_b32_e32 v51, v0
	v_mov_b32_e32 v52, v0
	v_mov_b32_e32 v53, v0
	v_mov_b32_e32 v54, v0
	v_mov_b32_e32 v55, v0
	v_mov_b32_e32 v8, v0
	v_mov_b32_e32 v9, v0
	v_mov_b32_e32 v10, v0
	v_mov_b32_e32 v11, v0
	v_mov_b32_e32 v12, v0
	v_mov_b32_e32 v13, v0
	v_mov_b32_e32 v14, v0
	v_mov_b32_e32 v15, v0
	v_mov_b32_e32 v24, v0
	v_mov_b32_e32 v25, v0
	v_mov_b32_e32 v26, v0
	v_mov_b32_e32 v27, v0
	v_mov_b32_e32 v28, v0
	v_mov_b32_e32 v29, v0
	v_mov_b32_e32 v30, v0
	v_mov_b32_e32 v31, v0
	v_mov_b32_e32 v40, v0
	v_mov_b32_e32 v41, v0
	v_mov_b32_e32 v42, v0
	v_mov_b32_e32 v43, v0
	v_mov_b32_e32 v44, v0
	v_mov_b32_e32 v45, v0
	v_mov_b32_e32 v46, v0
	v_mov_b32_e32 v47, v0
	v_mov_b32_e32 v56, v0
	v_mov_b32_e32 v57, v0
	v_mov_b32_e32 v58, v0
	v_mov_b32_e32 v59, v0
	v_mov_b32_e32 v60, v0
	v_mov_b32_e32 v61, v0
	v_mov_b32_e32 v62, v0
	v_mov_b32_e32 v63, v0
	v_mov_b32_e32 v64, v0
	v_mov_b32_e32 v65, v0
	v_mov_b32_e32 v66, v0
	v_mov_b32_e32 v67, v0
	v_mov_b32_e32 v68, v0
	v_mov_b32_e32 v69, v0
	v_mov_b32_e32 v70, v0
	v_mov_b32_e32 v71, v0
	v_mov_b32_e32 v80, v0
	v_mov_b32_e32 v81, v0
	v_mov_b32_e32 v82, v0
	v_mov_b32_e32 v83, v0
	v_mov_b32_e32 v84, v0
	v_mov_b32_e32 v85, v0
	v_mov_b32_e32 v86, v0
	v_mov_b32_e32 v87, v0
	v_mov_b32_e32 v96, v0
	v_mov_b32_e32 v97, v0
	s_nop 0
	v_mov_b32_e32 v98, v0
	v_mov_b32_e32 v99, v0
	v_mov_b32_e32 v100, v0
	v_mov_b32_e32 v101, v0
	v_mov_b32_e32 v102, v0
	v_mov_b32_e32 v103, v0
	v_mov_b32_e32 v112, v0
	v_mov_b32_e32 v113, v0
	v_mov_b32_e32 v114, v0
	v_mov_b32_e32 v115, v0
	v_mov_b32_e32 v116, v0
	v_mov_b32_e32 v117, v0
	v_mov_b32_e32 v118, v0
	v_mov_b32_e32 v119, v0
	v_mov_b32_e32 v72, v0
	v_mov_b32_e32 v73, v0
	v_mov_b32_e32 v74, v0
	v_mov_b32_e32 v75, v0
	v_mov_b32_e32 v76, v0
	v_mov_b32_e32 v77, v0
	v_mov_b32_e32 v78, v0
	v_mov_b32_e32 v79, v0
	v_mov_b32_e32 v88, v0
	v_mov_b32_e32 v89, v0
	v_mov_b32_e32 v90, v0
	v_mov_b32_e32 v91, v0
	v_mov_b32_e32 v92, v0
	v_mov_b32_e32 v93, v0
	v_mov_b32_e32 v94, v0
	v_mov_b32_e32 v95, v0
	v_mov_b32_e32 v104, v0
	v_mov_b32_e32 v105, v0
	v_mov_b32_e32 v106, v0
	v_mov_b32_e32 v107, v0
	v_mov_b32_e32 v108, v0
	v_mov_b32_e32 v109, v0
	v_mov_b32_e32 v110, v0
	v_mov_b32_e32 v111, v0
	v_mov_b32_e32 v120, v0
	v_mov_b32_e32 v121, v0
	v_mov_b32_e32 v122, v0
	v_mov_b32_e32 v123, v0
	v_mov_b32_e32 v124, v0
	v_mov_b32_e32 v125, v0
	v_mov_b32_e32 v126, v0
	v_mov_b32_e32 v127, v0

.LBB0_991:
	s_ashr_i32 s21, s20, 31
	s_lshl_b64 s[22:23], s[20:21], 19
	s_add_u32 s22, s72, s22
	s_addc_u32 s23, s73, s23
	s_and_b64 s[24:25], s[4:5], exec
	s_cselect_b32 s21, s23, s31
	s_cselect_b32 s51, s22, s30
	s_ashr_i32 s19, s18, 31
	s_lshl_b64 s[24:25], s[18:19], 19
	s_add_u32 s24, s70, s24
	s_addc_u32 s25, s71, s25
	s_and_b64 s[52:53], s[4:5], exec
	s_cselect_b32 s19, s25, s29
	s_cselect_b32 s52, s24, s28
	v_lshl_add_u32 v144, s26, 8, v148
	s_add_u32 s26, s30, 0x40080
	s_addc_u32 s27, s31, 0
	v_ashrrev_i32_e32 v145, 31, v144
	s_add_u32 s53, s28, 0x100
	v_mov_b32_e32 v0, 0
	v_lshl_add_u64 v[146:147], v[144:145], 2, s[78:79]
	s_addc_u32 s54, s29, 0
	s_mov_b32 s55, -2
	v_mov_b32_e32 v1, v0
	v_mov_b32_e32 v2, v0
	v_mov_b32_e32 v3, v0
	v_mov_b32_e32 v4, v0
	v_mov_b32_e32 v5, v0
	v_mov_b32_e32 v6, v0
	v_mov_b32_e32 v7, v0
	v_mov_b32_e32 v16, v0
	v_mov_b32_e32 v17, v0
	v_mov_b32_e32 v18, v0
	v_mov_b32_e32 v19, v0
	v_mov_b32_e32 v20, v0
	v_mov_b32_e32 v21, v0
	v_mov_b32_e32 v22, v0
	v_mov_b32_e32 v23, v0
	v_mov_b32_e32 v32, v0
	v_mov_b32_e32 v33, v0
	v_mov_b32_e32 v34, v0
	v_mov_b32_e32 v35, v0
	v_mov_b32_e32 v36, v0
	v_mov_b32_e32 v37, v0
	v_mov_b32_e32 v38, v0
	v_mov_b32_e32 v39, v0
	v_mov_b32_e32 v48, v0
	v_mov_b32_e32 v49, v0
	v_mov_b32_e32 v50, v0
	v_mov_b32_e32 v51, v0
	v_mov_b32_e32 v52, v0
	v_mov_b32_e32 v53, v0
	v_mov_b32_e32 v54, v0
	v_mov_b32_e32 v55, v0
	v_mov_b32_e32 v8, v0
	v_mov_b32_e32 v9, v0
	v_mov_b32_e32 v10, v0
	v_mov_b32_e32 v11, v0
	v_mov_b32_e32 v12, v0
	v_mov_b32_e32 v13, v0
	v_mov_b32_e32 v14, v0
	v_mov_b32_e32 v15, v0
	v_mov_b32_e32 v24, v0
	v_mov_b32_e32 v25, v0
	v_mov_b32_e32 v26, v0
	v_mov_b32_e32 v27, v0
	v_mov_b32_e32 v28, v0
	v_mov_b32_e32 v29, v0
	v_mov_b32_e32 v30, v0
	v_mov_b32_e32 v31, v0
	v_mov_b32_e32 v40, v0
	v_mov_b32_e32 v41, v0
	v_mov_b32_e32 v42, v0
	v_mov_b32_e32 v43, v0
	v_mov_b32_e32 v44, v0
	v_mov_b32_e32 v45, v0
	v_mov_b32_e32 v46, v0
	v_mov_b32_e32 v47, v0
	v_mov_b32_e32 v56, v0
	v_mov_b32_e32 v57, v0
	v_mov_b32_e32 v58, v0
	v_mov_b32_e32 v59, v0
	v_mov_b32_e32 v60, v0
	v_mov_b32_e32 v61, v0
	v_mov_b32_e32 v62, v0
	v_mov_b32_e32 v63, v0
	v_mov_b32_e32 v64, v0
	v_mov_b32_e32 v65, v0
	v_mov_b32_e32 v66, v0
	v_mov_b32_e32 v67, v0
	v_mov_b32_e32 v68, v0
	v_mov_b32_e32 v69, v0
	v_mov_b32_e32 v70, v0
	v_mov_b32_e32 v71, v0
	v_mov_b32_e32 v80, v0
	v_mov_b32_e32 v81, v0
	v_mov_b32_e32 v82, v0
	v_mov_b32_e32 v83, v0
	v_mov_b32_e32 v84, v0
	v_mov_b32_e32 v85, v0
	v_mov_b32_e32 v86, v0
	v_mov_b32_e32 v87, v0
	v_mov_b32_e32 v96, v0
	v_mov_b32_e32 v97, v0
	s_nop 0
	v_mov_b32_e32 v98, v0
	v_mov_b32_e32 v99, v0
	v_mov_b32_e32 v100, v0
	v_mov_b32_e32 v101, v0
	v_mov_b32_e32 v102, v0
	v_mov_b32_e32 v103, v0
	v_mov_b32_e32 v112, v0
	v_mov_b32_e32 v113, v0
	v_mov_b32_e32 v114, v0
	v_mov_b32_e32 v115, v0
	v_mov_b32_e32 v116, v0
	v_mov_b32_e32 v117, v0
	v_mov_b32_e32 v118, v0
	v_mov_b32_e32 v119, v0
	v_mov_b32_e32 v72, v0
	v_mov_b32_e32 v73, v0
	v_mov_b32_e32 v74, v0
	v_mov_b32_e32 v75, v0
	v_mov_b32_e32 v76, v0
	v_mov_b32_e32 v77, v0
	v_mov_b32_e32 v78, v0
	v_mov_b32_e32 v79, v0
	v_mov_b32_e32 v88, v0
	v_mov_b32_e32 v89, v0
	v_mov_b32_e32 v90, v0
	v_mov_b32_e32 v91, v0
	v_mov_b32_e32 v92, v0
	v_mov_b32_e32 v93, v0
	v_mov_b32_e32 v94, v0
	v_mov_b32_e32 v95, v0
	v_mov_b32_e32 v104, v0
	v_mov_b32_e32 v105, v0
	v_mov_b32_e32 v106, v0
	v_mov_b32_e32 v107, v0
	v_mov_b32_e32 v108, v0
	v_mov_b32_e32 v109, v0
	v_mov_b32_e32 v110, v0
	v_mov_b32_e32 v111, v0
	v_mov_b32_e32 v120, v0
	v_mov_b32_e32 v121, v0
	v_mov_b32_e32 v122, v0
	v_mov_b32_e32 v123, v0
	v_mov_b32_e32 v124, v0
	v_mov_b32_e32 v125, v0
	v_mov_b32_e32 v126, v0
	v_mov_b32_e32 v127, v0
	s_branch .LBB0_993

.LBB0_997:
	s_waitcnt vmcnt(16)
	v_fmamk_f32 v146, v160, 0x3a800000, v152
	v_rsq_f32_e32 v146, v146
	v_lshl_or_b32 v162, s50, 8, v150
	v_ashrrev_i32_e32 v163, 31, v162
	v_pk_mul_f32 v[126:127], v[146:147], v[126:127] op_sel_hi:[0,1]
	v_pk_mul_f32 v[124:125], v[146:147], v[124:125] op_sel_hi:[0,1]
	v_pk_mul_f32 v[120:121], v[146:147], v[120:121] op_sel_hi:[0,1]
	v_pk_mul_f32 v[122:123], v[146:147], v[122:123] op_sel_hi:[0,1]
	v_max_f32_e32 v124, 0, v124
	v_max_f32_e32 v120, 0, v120
	v_max_f32_e32 v125, 0, v125
	v_max_f32_e32 v121, 0, v121
	v_max_f32_e32 v126, 0, v126
	v_max_f32_e32 v127, 0, v127
	v_pk_mul_f32 v[124:125], v[124:125], v[124:125]
	v_pk_mul_f32 v[120:121], v[120:121], v[120:121]
	v_max_f32_e32 v122, 0, v122
	v_max_f32_e32 v123, 0, v123
	v_pk_mul_f32 v[126:127], v[126:127], v[126:127]
	v_pk_mul_f32 v[122:123], v[122:123], v[122:123]
	v_cvt_pk_bf16_f32 v124, v124, v125
	v_cvt_pk_bf16_f32 v125, v126, v127
	v_cvt_pk_bf16_f32 v126, v120, v121
	v_lshlrev_b64 v[120:121], 13, v[144:145]
	v_cvt_pk_bf16_f32 v127, v122, v123
	v_lshl_add_u64 v[120:121], s[74:75], 0, v[120:121]
	v_lshlrev_b64 v[122:123], 1, v[162:163]
	v_pk_mul_f32 v[116:117], v[146:147], v[116:117] op_sel_hi:[0,1]
	v_pk_mul_f32 v[112:113], v[146:147], v[112:113] op_sel_hi:[0,1]
	v_lshl_add_u64 v[120:121], v[120:121], 0, v[122:123]
	v_pk_mul_f32 v[118:119], v[146:147], v[118:119] op_sel_hi:[0,1]
	v_max_f32_e32 v116, 0, v116
	v_max_f32_e32 v112, 0, v112
	v_max_f32_e32 v117, 0, v117
	v_max_f32_e32 v113, 0, v113
	global_store_dwordx4 v[120:121], v[124:127], off
	v_pk_mul_f32 v[116:117], v[116:117], v[116:117]
	v_pk_mul_f32 v[114:115], v[146:147], v[114:115] op_sel_hi:[0,1]
	v_pk_mul_f32 v[124:125], v[112:113], v[112:113]
	v_max_f32_e32 v112, 0, v118
	v_max_f32_e32 v113, 0, v119
	v_pk_mul_f32 v[118:119], v[112:113], v[112:113]
	v_cvt_pk_bf16_f32 v112, v116, v117
	v_fmamk_f32 v116, v159, 0x3a800000, v152
	v_rsq_f32_e32 v116, v116
	v_max_f32_e32 v114, 0, v114
	v_max_f32_e32 v115, 0, v115
	v_pk_mul_f32 v[126:127], v[114:115], v[114:115]
	v_cvt_pk_bf16_f32 v113, v118, v119
	v_cvt_pk_bf16_f32 v114, v124, v125
	v_cvt_pk_bf16_f32 v115, v126, v127
	v_pk_mul_f32 v[108:109], v[116:117], v[108:109] op_sel_hi:[0,1]
	v_pk_mul_f32 v[104:105], v[116:117], v[104:105] op_sel_hi:[0,1]
	global_store_dwordx4 v[120:121], v[112:115], off offset:256
	v_pk_mul_f32 v[110:111], v[116:117], v[110:111] op_sel_hi:[0,1]
	v_max_f32_e32 v108, 0, v108
	v_or_b32_e32 v112, 16, v144
	v_max_f32_e32 v104, 0, v104
	v_max_f32_e32 v109, 0, v109
	v_max_f32_e32 v105, 0, v105
	v_ashrrev_i32_e32 v113, 31, v112
	v_pk_mul_f32 v[106:107], v[116:117], v[106:107] op_sel_hi:[0,1]
	v_pk_mul_f32 v[108:109], v[108:109], v[108:109]
	v_pk_mul_f32 v[114:115], v[104:105], v[104:105]
	v_max_f32_e32 v104, 0, v110
	v_max_f32_e32 v105, 0, v111
	v_max_f32_e32 v106, 0, v106
	v_max_f32_e32 v107, 0, v107
	v_pk_mul_f32 v[110:111], v[104:105], v[104:105]
	v_cvt_pk_bf16_f32 v104, v108, v109
	v_lshlrev_b64 v[108:109], 13, v[112:113]
	v_pk_mul_f32 v[118:119], v[106:107], v[106:107]
	v_lshl_add_u64 v[108:109], s[74:75], 0, v[108:109]
	v_pk_mul_f32 v[100:101], v[116:117], v[100:101] op_sel_hi:[0,1]
	v_pk_mul_f32 v[96:97], v[116:117], v[96:97] op_sel_hi:[0,1]
	v_cvt_pk_bf16_f32 v105, v110, v111
	v_cvt_pk_bf16_f32 v106, v114, v115
	v_cvt_pk_bf16_f32 v107, v118, v119
	v_lshl_add_u64 v[108:109], v[108:109], 0, v[122:123]
	v_pk_mul_f32 v[102:103], v[116:117], v[102:103] op_sel_hi:[0,1]
	v_max_f32_e32 v100, 0, v100
	v_max_f32_e32 v96, 0, v96
	v_max_f32_e32 v101, 0, v101
	v_max_f32_e32 v97, 0, v97
	global_store_dwordx4 v[108:109], v[104:107], off
	v_pk_mul_f32 v[100:101], v[100:101], v[100:101]
	v_pk_mul_f32 v[98:99], v[116:117], v[98:99] op_sel_hi:[0,1]
	v_pk_mul_f32 v[104:105], v[96:97], v[96:97]
	v_max_f32_e32 v96, 0, v102
	v_max_f32_e32 v97, 0, v103
	v_pk_mul_f32 v[102:103], v[96:97], v[96:97]
	v_cvt_pk_bf16_f32 v96, v100, v101
	v_fmamk_f32 v100, v158, 0x3a800000, v152
	v_rsq_f32_e32 v100, v100
	v_max_f32_e32 v98, 0, v98
	v_max_f32_e32 v99, 0, v99
	v_pk_mul_f32 v[106:107], v[98:99], v[98:99]
	v_cvt_pk_bf16_f32 v97, v102, v103
	v_cvt_pk_bf16_f32 v98, v104, v105
	v_cvt_pk_bf16_f32 v99, v106, v107
	v_pk_mul_f32 v[92:93], v[100:101], v[92:93] op_sel_hi:[0,1]
	v_pk_mul_f32 v[88:89], v[100:101], v[88:89] op_sel_hi:[0,1]
	global_store_dwordx4 v[108:109], v[96:99], off offset:256
	v_pk_mul_f32 v[94:95], v[100:101], v[94:95] op_sel_hi:[0,1]
	v_max_f32_e32 v92, 0, v92
	v_or_b32_e32 v96, 32, v144
	v_max_f32_e32 v88, 0, v88
	v_max_f32_e32 v93, 0, v93
	v_max_f32_e32 v89, 0, v89
	v_ashrrev_i32_e32 v97, 31, v96
	v_pk_mul_f32 v[90:91], v[100:101], v[90:91] op_sel_hi:[0,1]
	v_pk_mul_f32 v[92:93], v[92:93], v[92:93]
	v_pk_mul_f32 v[98:99], v[88:89], v[88:89]
	v_max_f32_e32 v88, 0, v94
	v_max_f32_e32 v89, 0, v95
	v_max_f32_e32 v90, 0, v90
	v_max_f32_e32 v91, 0, v91
	v_pk_mul_f32 v[94:95], v[88:89], v[88:89]
	v_cvt_pk_bf16_f32 v88, v92, v93
	v_lshlrev_b64 v[92:93], 13, v[96:97]
	v_pk_mul_f32 v[102:103], v[90:91], v[90:91]
	v_lshl_add_u64 v[92:93], s[74:75], 0, v[92:93]
	v_pk_mul_f32 v[84:85], v[100:101], v[84:85] op_sel_hi:[0,1]
	v_pk_mul_f32 v[80:81], v[100:101], v[80:81] op_sel_hi:[0,1]
	v_cvt_pk_bf16_f32 v89, v94, v95
	v_cvt_pk_bf16_f32 v90, v98, v99
	v_cvt_pk_bf16_f32 v91, v102, v103
	v_lshl_add_u64 v[92:93], v[92:93], 0, v[122:123]
	v_pk_mul_f32 v[86:87], v[100:101], v[86:87] op_sel_hi:[0,1]
	v_max_f32_e32 v84, 0, v84
	v_max_f32_e32 v80, 0, v80
	v_max_f32_e32 v85, 0, v85
	v_max_f32_e32 v81, 0, v81
	global_store_dwordx4 v[92:93], v[88:91], off
	v_pk_mul_f32 v[84:85], v[84:85], v[84:85]
	v_pk_mul_f32 v[82:83], v[100:101], v[82:83] op_sel_hi:[0,1]
	v_pk_mul_f32 v[88:89], v[80:81], v[80:81]
	v_max_f32_e32 v80, 0, v86
	v_max_f32_e32 v81, 0, v87
	v_pk_mul_f32 v[86:87], v[80:81], v[80:81]
	v_cvt_pk_bf16_f32 v80, v84, v85
	v_fmamk_f32 v84, v157, 0x3a800000, v152
	v_rsq_f32_e32 v84, v84
	v_max_f32_e32 v82, 0, v82
	v_max_f32_e32 v83, 0, v83
	v_pk_mul_f32 v[90:91], v[82:83], v[82:83]
	v_cvt_pk_bf16_f32 v81, v86, v87
	v_cvt_pk_bf16_f32 v82, v88, v89
	v_cvt_pk_bf16_f32 v83, v90, v91
	v_pk_mul_f32 v[76:77], v[84:85], v[76:77] op_sel_hi:[0,1]
	v_pk_mul_f32 v[72:73], v[84:85], v[72:73] op_sel_hi:[0,1]
	global_store_dwordx4 v[92:93], v[80:83], off offset:256
	v_pk_mul_f32 v[78:79], v[84:85], v[78:79] op_sel_hi:[0,1]
	v_max_f32_e32 v76, 0, v76
	v_or_b32_e32 v80, 48, v144
	v_max_f32_e32 v72, 0, v72
	v_max_f32_e32 v77, 0, v77
	v_max_f32_e32 v73, 0, v73
	v_ashrrev_i32_e32 v81, 31, v80
	v_pk_mul_f32 v[74:75], v[84:85], v[74:75] op_sel_hi:[0,1]
	v_pk_mul_f32 v[76:77], v[76:77], v[76:77]
	v_pk_mul_f32 v[82:83], v[72:73], v[72:73]
	v_max_f32_e32 v72, 0, v78
	v_max_f32_e32 v73, 0, v79
	v_max_f32_e32 v74, 0, v74
	v_max_f32_e32 v75, 0, v75
	v_pk_mul_f32 v[78:79], v[72:73], v[72:73]
	v_cvt_pk_bf16_f32 v72, v76, v77
	v_lshlrev_b64 v[76:77], 13, v[80:81]
	v_pk_mul_f32 v[86:87], v[74:75], v[74:75]
	v_lshl_add_u64 v[76:77], s[74:75], 0, v[76:77]
	v_pk_mul_f32 v[68:69], v[84:85], v[68:69] op_sel_hi:[0,1]
	v_pk_mul_f32 v[66:67], v[84:85], v[66:67] op_sel_hi:[0,1]
	v_pk_mul_f32 v[64:65], v[84:85], v[64:65] op_sel_hi:[0,1]
	v_cvt_pk_bf16_f32 v73, v78, v79
	v_cvt_pk_bf16_f32 v74, v82, v83
	v_cvt_pk_bf16_f32 v75, v86, v87
	v_lshl_add_u64 v[76:77], v[76:77], 0, v[122:123]
	v_pk_mul_f32 v[70:71], v[84:85], v[70:71] op_sel_hi:[0,1]
	v_max_f32_e32 v68, 0, v68
	v_max_f32_e32 v64, 0, v64
	v_max_f32_e32 v69, 0, v69
	v_max_f32_e32 v65, 0, v65
	v_max_f32_e32 v66, 0, v66
	v_max_f32_e32 v67, 0, v67
	global_store_dwordx4 v[76:77], v[72:75], off
	v_pk_mul_f32 v[68:69], v[68:69], v[68:69]
	s_nop 0
	v_pk_mul_f32 v[72:73], v[64:65], v[64:65]
	v_max_f32_e32 v64, 0, v70
	v_max_f32_e32 v65, 0, v71
	v_pk_mul_f32 v[74:75], v[66:67], v[66:67]
	v_fmamk_f32 v66, v156, 0x3a800000, v152
	v_pk_mul_f32 v[70:71], v[64:65], v[64:65]
	v_cvt_pk_bf16_f32 v64, v68, v69
	v_rsq_f32_e32 v68, v66
	v_cvt_pk_bf16_f32 v65, v70, v71
	v_cvt_pk_bf16_f32 v66, v72, v73
	v_cvt_pk_bf16_f32 v67, v74, v75
	v_pk_mul_f32 v[56:57], v[68:69], v[56:57] op_sel_hi:[0,1]
	v_pk_mul_f32 v[62:63], v[68:69], v[62:63] op_sel_hi:[0,1]
	v_max_f32_e32 v56, 0, v56
	v_max_f32_e32 v57, 0, v57
	global_store_dwordx4 v[76:77], v[64:67], off offset:256
	v_pk_mul_f32 v[60:61], v[68:69], v[60:61] op_sel_hi:[0,1]
	v_pk_mul_f32 v[58:59], v[68:69], v[58:59] op_sel_hi:[0,1]
	v_pk_mul_f32 v[64:65], v[56:57], v[56:57]
	v_max_f32_e32 v56, 0, v62
	v_max_f32_e32 v57, 0, v63
	v_max_f32_e32 v60, 0, v60
	v_max_f32_e32 v61, 0, v61
	v_max_f32_e32 v58, 0, v58
	v_max_f32_e32 v59, 0, v59
	v_pk_mul_f32 v[62:63], v[56:57], v[56:57]
	v_pk_mul_f32 v[60:61], v[60:61], v[60:61]
	v_pk_mul_f32 v[66:67], v[58:59], v[58:59]
	v_cvt_pk_bf16_f32 v57, v62, v63
	v_add_co_u32_e32 v62, vcc, s46, v120
	v_pk_mul_f32 v[52:53], v[68:69], v[52:53] op_sel_hi:[0,1]
	v_pk_mul_f32 v[50:51], v[68:69], v[50:51] op_sel_hi:[0,1]
	v_pk_mul_f32 v[48:49], v[68:69], v[48:49] op_sel_hi:[0,1]
	v_cvt_pk_bf16_f32 v56, v60, v61
	v_cvt_pk_bf16_f32 v58, v64, v65
	v_cvt_pk_bf16_f32 v59, v66, v67
	v_addc_co_u32_e32 v63, vcc, 0, v121, vcc
	v_pk_mul_f32 v[54:55], v[68:69], v[54:55] op_sel_hi:[0,1]
	v_max_f32_e32 v52, 0, v52
	v_max_f32_e32 v48, 0, v48
	v_max_f32_e32 v53, 0, v53
	v_max_f32_e32 v49, 0, v49
	v_max_f32_e32 v50, 0, v50
	v_max_f32_e32 v51, 0, v51
	global_store_dwordx4 v[62:63], v[56:59], off
	v_pk_mul_f32 v[52:53], v[52:53], v[52:53]
	v_lshl_add_u64 v[60:61], v[120:121], 0, s[10:11]
	v_pk_mul_f32 v[56:57], v[48:49], v[48:49]
	v_max_f32_e32 v48, 0, v54
	v_max_f32_e32 v49, 0, v55
	v_pk_mul_f32 v[58:59], v[50:51], v[50:51]
	v_fmamk_f32 v50, v155, 0x3a800000, v152
	v_pk_mul_f32 v[54:55], v[48:49], v[48:49]
	v_cvt_pk_bf16_f32 v48, v52, v53
	v_rsq_f32_e32 v52, v50
	v_cvt_pk_bf16_f32 v49, v54, v55
	v_cvt_pk_bf16_f32 v50, v56, v57
	v_cvt_pk_bf16_f32 v51, v58, v59
	v_pk_mul_f32 v[40:41], v[52:53], v[40:41] op_sel_hi:[0,1]
	v_pk_mul_f32 v[46:47], v[52:53], v[46:47] op_sel_hi:[0,1]
	v_max_f32_e32 v40, 0, v40
	v_max_f32_e32 v41, 0, v41
	global_store_dwordx4 v[60:61], v[48:51], off offset:256
	v_pk_mul_f32 v[44:45], v[52:53], v[44:45] op_sel_hi:[0,1]
	v_pk_mul_f32 v[42:43], v[52:53], v[42:43] op_sel_hi:[0,1]
	v_pk_mul_f32 v[48:49], v[40:41], v[40:41]
	v_max_f32_e32 v40, 0, v46
	v_max_f32_e32 v41, 0, v47
	v_max_f32_e32 v44, 0, v44
	v_max_f32_e32 v45, 0, v45
	v_max_f32_e32 v42, 0, v42
	v_max_f32_e32 v43, 0, v43
	v_pk_mul_f32 v[46:47], v[40:41], v[40:41]
	v_pk_mul_f32 v[44:45], v[44:45], v[44:45]
	v_pk_mul_f32 v[50:51], v[42:43], v[42:43]
	v_cvt_pk_bf16_f32 v41, v46, v47
	v_add_co_u32_e32 v46, vcc, s47, v120
	v_pk_mul_f32 v[36:37], v[52:53], v[36:37] op_sel_hi:[0,1]
	v_pk_mul_f32 v[34:35], v[52:53], v[34:35] op_sel_hi:[0,1]
	v_pk_mul_f32 v[32:33], v[52:53], v[32:33] op_sel_hi:[0,1]
	v_cvt_pk_bf16_f32 v40, v44, v45
	v_cvt_pk_bf16_f32 v42, v48, v49
	v_cvt_pk_bf16_f32 v43, v50, v51
	v_addc_co_u32_e32 v47, vcc, 0, v121, vcc
	v_pk_mul_f32 v[38:39], v[52:53], v[38:39] op_sel_hi:[0,1]
	v_max_f32_e32 v36, 0, v36
	v_max_f32_e32 v32, 0, v32
	v_max_f32_e32 v37, 0, v37
	v_max_f32_e32 v33, 0, v33
	v_max_f32_e32 v34, 0, v34
	v_max_f32_e32 v35, 0, v35
	global_store_dwordx4 v[46:47], v[40:43], off
	v_pk_mul_f32 v[36:37], v[36:37], v[36:37]
	v_lshl_add_u64 v[44:45], v[120:121], 0, s[12:13]
	v_pk_mul_f32 v[40:41], v[32:33], v[32:33]
	v_max_f32_e32 v32, 0, v38
	v_max_f32_e32 v33, 0, v39
	v_pk_mul_f32 v[42:43], v[34:35], v[34:35]
	v_fmamk_f32 v34, v154, 0x3a800000, v152
	v_pk_mul_f32 v[38:39], v[32:33], v[32:33]
	v_cvt_pk_bf16_f32 v32, v36, v37
	v_rsq_f32_e32 v36, v34
	v_cvt_pk_bf16_f32 v33, v38, v39
	v_cvt_pk_bf16_f32 v34, v40, v41
	v_cvt_pk_bf16_f32 v35, v42, v43
	v_pk_mul_f32 v[24:25], v[36:37], v[24:25] op_sel_hi:[0,1]
	v_pk_mul_f32 v[30:31], v[36:37], v[30:31] op_sel_hi:[0,1]
	v_max_f32_e32 v24, 0, v24
	v_max_f32_e32 v25, 0, v25
	global_store_dwordx4 v[44:45], v[32:35], off offset:256
	v_pk_mul_f32 v[28:29], v[36:37], v[28:29] op_sel_hi:[0,1]
	v_pk_mul_f32 v[26:27], v[36:37], v[26:27] op_sel_hi:[0,1]
	v_pk_mul_f32 v[32:33], v[24:25], v[24:25]
	v_max_f32_e32 v24, 0, v30
	v_max_f32_e32 v25, 0, v31
	v_max_f32_e32 v28, 0, v28
	v_max_f32_e32 v29, 0, v29
	v_max_f32_e32 v26, 0, v26
	v_max_f32_e32 v27, 0, v27
	v_pk_mul_f32 v[30:31], v[24:25], v[24:25]
	v_pk_mul_f32 v[28:29], v[28:29], v[28:29]
	v_pk_mul_f32 v[34:35], v[26:27], v[26:27]
	v_cvt_pk_bf16_f32 v25, v30, v31
	v_add_co_u32_e32 v30, vcc, s48, v120
	v_pk_mul_f32 v[20:21], v[36:37], v[20:21] op_sel_hi:[0,1]
	v_pk_mul_f32 v[18:19], v[36:37], v[18:19] op_sel_hi:[0,1]
	v_pk_mul_f32 v[16:17], v[36:37], v[16:17] op_sel_hi:[0,1]
	v_cvt_pk_bf16_f32 v24, v28, v29
	v_cvt_pk_bf16_f32 v26, v32, v33
	v_cvt_pk_bf16_f32 v27, v34, v35
	v_addc_co_u32_e32 v31, vcc, 0, v121, vcc
	v_pk_mul_f32 v[22:23], v[36:37], v[22:23] op_sel_hi:[0,1]
	v_max_f32_e32 v20, 0, v20
	v_max_f32_e32 v16, 0, v16
	v_max_f32_e32 v21, 0, v21
	v_max_f32_e32 v17, 0, v17
	v_max_f32_e32 v18, 0, v18
	v_max_f32_e32 v19, 0, v19
	global_store_dwordx4 v[30:31], v[24:27], off
	v_pk_mul_f32 v[20:21], v[20:21], v[20:21]
	v_lshl_add_u64 v[28:29], v[120:121], 0, s[14:15]
	v_pk_mul_f32 v[24:25], v[16:17], v[16:17]
	v_max_f32_e32 v16, 0, v22
	v_max_f32_e32 v17, 0, v23
	v_pk_mul_f32 v[26:27], v[18:19], v[18:19]
	v_fmamk_f32 v18, v153, 0x3a800000, v152
	v_pk_mul_f32 v[22:23], v[16:17], v[16:17]
	v_cvt_pk_bf16_f32 v16, v20, v21
	v_rsq_f32_e32 v20, v18
	v_cvt_pk_bf16_f32 v17, v22, v23
	v_cvt_pk_bf16_f32 v18, v24, v25
	v_cvt_pk_bf16_f32 v19, v26, v27
	v_pk_mul_f32 v[8:9], v[20:21], v[8:9] op_sel_hi:[0,1]
	v_pk_mul_f32 v[14:15], v[20:21], v[14:15] op_sel_hi:[0,1]
	v_max_f32_e32 v8, 0, v8
	v_max_f32_e32 v9, 0, v9
	global_store_dwordx4 v[28:29], v[16:19], off offset:256
	v_pk_mul_f32 v[12:13], v[20:21], v[12:13] op_sel_hi:[0,1]
	v_pk_mul_f32 v[10:11], v[20:21], v[10:11] op_sel_hi:[0,1]
	v_pk_mul_f32 v[16:17], v[8:9], v[8:9]
	v_max_f32_e32 v8, 0, v14
	v_max_f32_e32 v9, 0, v15
	v_max_f32_e32 v12, 0, v12
	v_max_f32_e32 v13, 0, v13
	v_max_f32_e32 v10, 0, v10
	v_max_f32_e32 v11, 0, v11
	v_pk_mul_f32 v[14:15], v[8:9], v[8:9]
	v_pk_mul_f32 v[12:13], v[12:13], v[12:13]
	v_pk_mul_f32 v[18:19], v[10:11], v[10:11]
	v_cvt_pk_bf16_f32 v9, v14, v15
	v_add_co_u32_e32 v14, vcc, s49, v120
	v_pk_mul_f32 v[0:1], v[20:21], v[0:1] op_sel_hi:[0,1]
	v_cvt_pk_bf16_f32 v8, v12, v13
	v_cvt_pk_bf16_f32 v10, v16, v17
	v_cvt_pk_bf16_f32 v11, v18, v19
	v_addc_co_u32_e32 v15, vcc, 0, v121, vcc
	v_pk_mul_f32 v[6:7], v[20:21], v[6:7] op_sel_hi:[0,1]
	v_pk_mul_f32 v[4:5], v[20:21], v[4:5] op_sel_hi:[0,1]
	v_pk_mul_f32 v[2:3], v[20:21], v[2:3] op_sel_hi:[0,1]
	v_max_f32_e32 v0, 0, v0
	v_max_f32_e32 v1, 0, v1
	global_store_dwordx4 v[14:15], v[8:11], off
	v_max_f32_e32 v4, 0, v4
	v_max_f32_e32 v5, 0, v5
	v_pk_mul_f32 v[8:9], v[0:1], v[0:1]
	v_max_f32_e32 v0, 0, v6
	v_max_f32_e32 v2, 0, v2
	v_max_f32_e32 v1, 0, v7
	v_max_f32_e32 v3, 0, v3
	v_pk_mul_f32 v[4:5], v[4:5], v[4:5]
	v_pk_mul_f32 v[6:7], v[0:1], v[0:1]
	v_pk_mul_f32 v[10:11], v[2:3], v[2:3]
	v_lshl_add_u64 v[12:13], v[120:121], 0, s[16:17]
	v_cvt_pk_bf16_f32 v0, v4, v5
	v_cvt_pk_bf16_f32 v1, v6, v7
	v_cvt_pk_bf16_f32 v2, v8, v9
	v_cvt_pk_bf16_f32 v3, v10, v11
	s_andn2_b64 vcc, exec, s[4:5]
	s_mov_b64 s[4:5], -1
	global_store_dwordx4 v[12:13], v[0:3], off offset:256
	s_cbranch_vccnz .LBB0_984
	s_andn2_b64 vcc, exec, s[2:3]
	s_cbranch_vccnz .LBB0_983
	s_barrier
	s_branch .LBB0_983

.LBB0_1069:
	s_ashr_i32 s11, s10, 31
	s_lshl_b64 s[12:13], s[10:11], 21
	s_add_u32 s12, s74, s12
	s_addc_u32 s13, s75, s13
	s_and_b64 s[14:15], s[0:1], exec
	s_cselect_b32 s11, s13, s19
	s_cselect_b32 s37, s12, s18
	s_ashr_i32 s9, s8, 31
	s_lshl_b64 s[14:15], s[8:9], 21
	s_add_u32 s14, s46, s14
	s_addc_u32 s15, s47, s15
	s_and_b64 s[22:23], s[0:1], exec
	s_cselect_b32 s9, s15, s21
	s_cselect_b32 s38, s14, s20
	s_add_u32 s18, s18, 0x100080
	s_addc_u32 s19, s19, 0
	s_add_u32 s39, s20, 0x100
	v_mov_b32_e32 v0, 0
	s_addc_u32 s40, s21, 0
	s_mov_b32 s41, -2
	v_mov_b32_e32 v1, v0
	v_mov_b32_e32 v2, v0
	v_mov_b32_e32 v3, v0
	v_mov_b32_e32 v4, v0
	v_mov_b32_e32 v5, v0
	v_mov_b32_e32 v6, v0
	v_mov_b32_e32 v7, v0
	v_mov_b32_e32 v12, v0
	v_mov_b32_e32 v13, v0
	v_mov_b32_e32 v14, v0
	v_mov_b32_e32 v15, v0
	v_mov_b32_e32 v20, v0
	v_mov_b32_e32 v21, v0
	v_mov_b32_e32 v22, v0
	v_mov_b32_e32 v23, v0
	v_mov_b32_e32 v28, v0
	v_mov_b32_e32 v29, v0
	v_mov_b32_e32 v30, v0
	v_mov_b32_e32 v31, v0
	v_mov_b32_e32 v36, v0
	v_mov_b32_e32 v37, v0
	v_mov_b32_e32 v38, v0
	v_mov_b32_e32 v39, v0
	v_mov_b32_e32 v44, v0
	v_mov_b32_e32 v45, v0
	v_mov_b32_e32 v46, v0
	v_mov_b32_e32 v47, v0
	v_mov_b32_e32 v52, v0
	v_mov_b32_e32 v53, v0
	v_mov_b32_e32 v54, v0
	v_mov_b32_e32 v55, v0
	v_mov_b32_e32 v8, v0
	v_mov_b32_e32 v9, v0
	v_mov_b32_e32 v10, v0
	v_mov_b32_e32 v11, v0
	v_mov_b32_e32 v16, v0
	v_mov_b32_e32 v17, v0
	v_mov_b32_e32 v18, v0
	v_mov_b32_e32 v19, v0
	v_mov_b32_e32 v24, v0
	v_mov_b32_e32 v25, v0
	v_mov_b32_e32 v26, v0
	v_mov_b32_e32 v27, v0
	v_mov_b32_e32 v32, v0
	v_mov_b32_e32 v33, v0
	v_mov_b32_e32 v34, v0
	v_mov_b32_e32 v35, v0
	v_mov_b32_e32 v40, v0
	v_mov_b32_e32 v41, v0
	v_mov_b32_e32 v42, v0
	v_mov_b32_e32 v43, v0
	v_mov_b32_e32 v48, v0
	v_mov_b32_e32 v49, v0
	v_mov_b32_e32 v50, v0
	v_mov_b32_e32 v51, v0
	v_mov_b32_e32 v56, v0
	v_mov_b32_e32 v57, v0
	v_mov_b32_e32 v58, v0
	v_mov_b32_e32 v59, v0
	v_mov_b32_e32 v60, v0
	v_mov_b32_e32 v61, v0
	v_mov_b32_e32 v62, v0
	v_mov_b32_e32 v63, v0
	v_mov_b32_e32 v64, v0
	v_mov_b32_e32 v65, v0
	v_mov_b32_e32 v66, v0
	v_mov_b32_e32 v67, v0
	v_mov_b32_e32 v68, v0
	v_mov_b32_e32 v69, v0
	v_mov_b32_e32 v70, v0
	v_mov_b32_e32 v71, v0
	v_mov_b32_e32 v76, v0
	v_mov_b32_e32 v77, v0
	v_mov_b32_e32 v78, v0
	v_mov_b32_e32 v79, v0
	v_mov_b32_e32 v84, v0
	v_mov_b32_e32 v85, v0
	v_mov_b32_e32 v86, v0
	v_mov_b32_e32 v87, v0
	v_mov_b32_e32 v92, v0
	v_mov_b32_e32 v93, v0
	v_mov_b32_e32 v94, v0
	v_mov_b32_e32 v95, v0
	s_nop 0
	v_mov_b32_e32 v100, v0
	v_mov_b32_e32 v101, v0
	v_mov_b32_e32 v102, v0
	v_mov_b32_e32 v103, v0
	v_mov_b32_e32 v108, v0
	v_mov_b32_e32 v109, v0
	v_mov_b32_e32 v110, v0
	v_mov_b32_e32 v111, v0
	v_mov_b32_e32 v116, v0
	v_mov_b32_e32 v117, v0
	v_mov_b32_e32 v118, v0
	v_mov_b32_e32 v119, v0
	v_mov_b32_e32 v72, v0
	v_mov_b32_e32 v73, v0
	v_mov_b32_e32 v74, v0
	v_mov_b32_e32 v75, v0
	v_mov_b32_e32 v80, v0
	v_mov_b32_e32 v81, v0
	v_mov_b32_e32 v82, v0
	v_mov_b32_e32 v83, v0
	v_mov_b32_e32 v88, v0
	v_mov_b32_e32 v89, v0
	v_mov_b32_e32 v90, v0
	v_mov_b32_e32 v91, v0
	v_mov_b32_e32 v96, v0
	v_mov_b32_e32 v97, v0
	v_mov_b32_e32 v98, v0
	v_mov_b32_e32 v99, v0
	v_mov_b32_e32 v104, v0
	v_mov_b32_e32 v105, v0
	v_mov_b32_e32 v106, v0
	v_mov_b32_e32 v107, v0
	v_mov_b32_e32 v112, v0
	v_mov_b32_e32 v113, v0
	v_mov_b32_e32 v114, v0
	v_mov_b32_e32 v115, v0
	v_mov_b32_e32 v120, v0
	v_mov_b32_e32 v121, v0
	v_mov_b32_e32 v122, v0
	v_mov_b32_e32 v123, v0
	v_mov_b32_e32 v124, v0
	v_mov_b32_e32 v125, v0
	v_mov_b32_e32 v126, v0
	v_mov_b32_e32 v127, v0
